# speedup vs baseline: 1.0275x; 1.0014x over previous
; DEVI int lbid() { int t = blockIdx.x; asm volatile("" : "+s"(t)); return t; }
; DEVI int lgdim() { int t = gridDim.x; asm volatile("" : "+s"(t)); return t; }
; DEVI void prep_phase(const Params& p, char* lds) {
;     ...
;     for (int it = lbid(); it < 4 * 48; it += lgdim()) {
;       const int l = it / 48, n0 = (it % 48) * 128, kg = tid >> 7, col = tid & 127;
;       const float* W = p.in[I_MODW] + (size_t)l * 1024 * 6144 + n0 + col;
;       float a0 = 0.f, a1 = 0.f, a2 = 0.f;
; #pragma unroll 8
;       for (int k = kg * 256; k < kg * 256 + 256; ++k) { float w = W[(size_t)k * 6144]; a0 = fmaf(sv[k], w, a0); a1 = fmaf(sv[1024 + k], w, a1); a2 = fmaf(sv[2048 + k], w, a2); }
;       part[(kg * 3 + 0) * 128 + col] = a0; part[(kg * 3 + 1) * 128 + col] = a1; part[(kg * 3 + 2) * 128 + col] = a2;
.LBB0_3232:
	s_mov_b64 s[38:39], 0x6000
	s_mov_b32 s16, 0x2a000
	v_lshl_add_u64 v[58:59], v[6:7], 0, s[12:13]
	global_load_dword v70, v[58:59], off
	v_lshl_add_u64 v[58:59], v[58:59], 0, s[38:39]
	global_load_dword v71, v[58:59], off
	v_lshl_add_u64 v[58:59], v[58:59], 0, s[38:39]
	global_load_dword v72, v[58:59], off
	v_lshl_add_u64 v[58:59], v[58:59], 0, s[38:39]
	global_load_dword v73, v[58:59], off
	v_lshl_add_u64 v[58:59], v[58:59], 0, s[38:39]
	global_load_dword v74, v[58:59], off
	v_lshl_add_u64 v[58:59], v[58:59], 0, s[38:39]
	global_load_dword v75, v[58:59], off
	v_lshl_add_u64 v[58:59], v[58:59], 0, s[38:39]
	global_load_dword v76, v[58:59], off
	v_lshl_add_u64 v[58:59], v[58:59], 0, s[38:39]
	global_load_dword v77, v[58:59], off
	v_lshl_add_u64 v[58:59], v[58:59], 0, s[38:39]
	global_load_dword v78, v[58:59], off
	v_lshl_add_u64 v[58:59], v[58:59], 0, s[38:39]
	global_load_dword v79, v[58:59], off
	v_lshl_add_u64 v[58:59], v[58:59], 0, s[38:39]
	global_load_dword v80, v[58:59], off
	v_lshl_add_u64 v[58:59], v[58:59], 0, s[38:39]
	global_load_dword v81, v[58:59], off
	v_lshl_add_u64 v[58:59], v[58:59], 0, s[38:39]
	global_load_dword v82, v[58:59], off
	v_lshl_add_u64 v[58:59], v[58:59], 0, s[38:39]
	global_load_dword v83, v[58:59], off
	v_lshl_add_u64 v[58:59], v[58:59], 0, s[38:39]
	global_load_dword v84, v[58:59], off
	v_lshl_add_u64 v[58:59], v[58:59], 0, s[38:39]
	global_load_dword v85, v[58:59], off
	v_lshl_add_u64 v[58:59], v[58:59], 0, s[38:39]
	global_load_dword v86, v[58:59], off
	v_lshl_add_u64 v[58:59], v[58:59], 0, s[38:39]
	global_load_dword v87, v[58:59], off
	v_lshl_add_u64 v[58:59], v[58:59], 0, s[38:39]
	global_load_dword v88, v[58:59], off
	v_lshl_add_u64 v[58:59], v[58:59], 0, s[38:39]
	global_load_dword v89, v[58:59], off
	v_lshl_add_u64 v[58:59], v[58:59], 0, s[38:39]
	global_load_dword v90, v[58:59], off
	v_lshl_add_u64 v[58:59], v[58:59], 0, s[38:39]
	global_load_dword v91, v[58:59], off
	v_lshl_add_u64 v[58:59], v[58:59], 0, s[38:39]
	global_load_dword v92, v[58:59], off
	v_lshl_add_u64 v[58:59], v[58:59], 0, s[38:39]
	global_load_dword v93, v[58:59], off
	v_lshl_add_u64 v[58:59], v[58:59], 0, s[38:39]
	global_load_dword v94, v[58:59], off
	v_lshl_add_u64 v[58:59], v[58:59], 0, s[38:39]
	global_load_dword v95, v[58:59], off
	v_lshl_add_u64 v[58:59], v[58:59], 0, s[38:39]
	global_load_dword v96, v[58:59], off
	v_lshl_add_u64 v[58:59], v[58:59], 0, s[38:39]
	global_load_dword v97, v[58:59], off
	v_lshl_add_u64 v[58:59], v[58:59], 0, s[38:39]
	global_load_dword v98, v[58:59], off
	v_lshl_add_u64 v[58:59], v[58:59], 0, s[38:39]
	global_load_dword v99, v[58:59], off
	v_lshl_add_u64 v[58:59], v[58:59], 0, s[38:39]
	global_load_dword v100, v[58:59], off
	v_lshl_add_u64 v[58:59], v[58:59], 0, s[38:39]
	global_load_dword v101, v[58:59], off
	s_add_u32 s12, s12, 0xc0000
	s_addc_u32 s13, s13, 0
	ds_read_b128 v[16:19], v15 offset:0
	ds_read_b128 v[20:23], v15 offset:16
	ds_read_b128 v[24:27], v15 offset:4096
	ds_read_b128 v[28:31], v15 offset:4112
	ds_read_b128 v[32:35], v15 offset:8192
	ds_read_b128 v[36:39], v15 offset:8208
	s_waitcnt lgkmcnt(0)
	s_waitcnt vmcnt(31)
	v_fmac_f32_e32 v8, v16, v70
	v_fmac_f32_e32 v9, v24, v70
	v_fmac_f32_e32 v14, v32, v70
	s_waitcnt vmcnt(30)
	v_fmac_f32_e32 v8, v17, v71
	v_fmac_f32_e32 v9, v25, v71
	v_fmac_f32_e32 v14, v33, v71
	s_waitcnt vmcnt(29)
	v_fmac_f32_e32 v8, v18, v72
	v_fmac_f32_e32 v9, v26, v72
	v_fmac_f32_e32 v14, v34, v72
	s_waitcnt vmcnt(28)
	v_fmac_f32_e32 v8, v19, v73
	v_fmac_f32_e32 v9, v27, v73
	v_fmac_f32_e32 v14, v35, v73
	s_waitcnt vmcnt(27)
	v_fmac_f32_e32 v8, v20, v74
	v_fmac_f32_e32 v9, v28, v74
	v_fmac_f32_e32 v14, v36, v74
	s_waitcnt vmcnt(26)
	v_fmac_f32_e32 v8, v21, v75
	v_fmac_f32_e32 v9, v29, v75
	v_fmac_f32_e32 v14, v37, v75
	s_waitcnt vmcnt(25)
	v_fmac_f32_e32 v8, v22, v76
	v_fmac_f32_e32 v9, v30, v76
	v_fmac_f32_e32 v14, v38, v76
	s_waitcnt vmcnt(24)
	v_fmac_f32_e32 v8, v23, v77
	v_fmac_f32_e32 v9, v31, v77
	v_fmac_f32_e32 v14, v39, v77
	ds_read_b128 v[16:19], v15 offset:32
	ds_read_b128 v[20:23], v15 offset:48
	ds_read_b128 v[24:27], v15 offset:4128
	ds_read_b128 v[28:31], v15 offset:4144
	ds_read_b128 v[32:35], v15 offset:8224
	ds_read_b128 v[36:39], v15 offset:8240
	s_waitcnt lgkmcnt(0)
	s_waitcnt vmcnt(23)
	v_fmac_f32_e32 v8, v16, v78
	v_fmac_f32_e32 v9, v24, v78
	v_fmac_f32_e32 v14, v32, v78
	s_waitcnt vmcnt(22)
	v_fmac_f32_e32 v8, v17, v79
	v_fmac_f32_e32 v9, v25, v79
	v_fmac_f32_e32 v14, v33, v79
	s_waitcnt vmcnt(21)
; DEVI int lbid() { int t = blockIdx.x; asm volatile("" : "+s"(t)); return t; }
; DEVI int lgdim() { int t = gridDim.x; asm volatile("" : "+s"(t)); return t; }
; DEVI void prep_phase(const Params& p, char* lds) {
;     ...
;     for (int it = lbid(); it < 4 * 48; it += lgdim()) {
;       const int l = it / 48, n0 = (it % 48) * 128, kg = tid >> 7, col = tid & 127;
;       const float* W = p.in[I_MODW] + (size_t)l * 1024 * 6144 + n0 + col;
;       float a0 = 0.f, a1 = 0.f, a2 = 0.f;
; #pragma unroll 8
;       for (int k = kg * 256; k < kg * 256 + 256; ++k) { float w = W[(size_t)k * 6144]; a0 = fmaf(sv[k], w, a0); a1 = fmaf(sv[1024 + k], w, a1); a2 = fmaf(sv[2048 + k], w, a2); }
;       part[(kg * 3 + 0) * 128 + col] = a0; part[(kg * 3 + 1) * 128 + col] = a1; part[(kg * 3 + 2) * 128 + col] = a2;
;       __syncthreads();
;       if (tid < 384) {
;         const int v = tid >> 7;
;         float s = part[(0 * 3 + v) * 128 + col] + part[(1 * 3 + v) * 128 + col] + part[(2 * 3 + v) * 128 + col] + part[(3 * 3 + v) * 128 + col];
;         MOD[((size_t)l * 3 + v) * 6144 + n0 + col] = s + p.in[I_MODB][(size_t)l * 6144 + n0 + col];
;       }
;       __syncthreads();
	v_fmac_f32_e32 v8, v18, v80
	v_fmac_f32_e32 v9, v26, v80
	v_fmac_f32_e32 v14, v34, v80
	s_waitcnt vmcnt(20)
	v_fmac_f32_e32 v8, v19, v81
	v_fmac_f32_e32 v9, v27, v81
	v_fmac_f32_e32 v14, v35, v81
	s_waitcnt vmcnt(19)
	v_fmac_f32_e32 v8, v20, v82
	v_fmac_f32_e32 v9, v28, v82
	v_fmac_f32_e32 v14, v36, v82
	s_waitcnt vmcnt(18)
	v_fmac_f32_e32 v8, v21, v83
	v_fmac_f32_e32 v9, v29, v83
	v_fmac_f32_e32 v14, v37, v83
	s_waitcnt vmcnt(17)
	v_fmac_f32_e32 v8, v22, v84
	v_fmac_f32_e32 v9, v30, v84
	v_fmac_f32_e32 v14, v38, v84
	s_waitcnt vmcnt(16)
	v_fmac_f32_e32 v8, v23, v85
	v_fmac_f32_e32 v9, v31, v85
	v_fmac_f32_e32 v14, v39, v85
	ds_read_b128 v[16:19], v15 offset:64
	ds_read_b128 v[20:23], v15 offset:80
	ds_read_b128 v[24:27], v15 offset:4160
	ds_read_b128 v[28:31], v15 offset:4176
	ds_read_b128 v[32:35], v15 offset:8256
	ds_read_b128 v[36:39], v15 offset:8272
	s_waitcnt lgkmcnt(0)
	s_waitcnt vmcnt(15)
	v_fmac_f32_e32 v8, v16, v86
	v_fmac_f32_e32 v9, v24, v86
	v_fmac_f32_e32 v14, v32, v86
	s_waitcnt vmcnt(14)
	v_fmac_f32_e32 v8, v17, v87
	v_fmac_f32_e32 v9, v25, v87
	v_fmac_f32_e32 v14, v33, v87
	s_waitcnt vmcnt(13)
	v_fmac_f32_e32 v8, v18, v88
	v_fmac_f32_e32 v9, v26, v88
	v_fmac_f32_e32 v14, v34, v88
	s_waitcnt vmcnt(12)
	v_fmac_f32_e32 v8, v19, v89
	v_fmac_f32_e32 v9, v27, v89
	v_fmac_f32_e32 v14, v35, v89
	s_waitcnt vmcnt(11)
	v_fmac_f32_e32 v8, v20, v90
	v_fmac_f32_e32 v9, v28, v90
	v_fmac_f32_e32 v14, v36, v90
	s_waitcnt vmcnt(10)
	v_fmac_f32_e32 v8, v21, v91
	v_fmac_f32_e32 v9, v29, v91
	v_fmac_f32_e32 v14, v37, v91
	s_waitcnt vmcnt(9)
	v_fmac_f32_e32 v8, v22, v92
	v_fmac_f32_e32 v9, v30, v92
	v_fmac_f32_e32 v14, v38, v92
	s_waitcnt vmcnt(8)
	v_fmac_f32_e32 v8, v23, v93
	v_fmac_f32_e32 v9, v31, v93
	v_fmac_f32_e32 v14, v39, v93
	ds_read_b128 v[16:19], v15 offset:96
	ds_read_b128 v[20:23], v15 offset:112
	ds_read_b128 v[24:27], v15 offset:4192
	ds_read_b128 v[28:31], v15 offset:4208
	ds_read_b128 v[32:35], v15 offset:8288
	ds_read_b128 v[36:39], v15 offset:8304
	s_waitcnt lgkmcnt(0)
	s_waitcnt vmcnt(7)
	v_fmac_f32_e32 v8, v16, v94
	v_fmac_f32_e32 v9, v24, v94
	v_fmac_f32_e32 v14, v32, v94
	s_waitcnt vmcnt(6)
	v_fmac_f32_e32 v8, v17, v95
	v_fmac_f32_e32 v9, v25, v95
	v_fmac_f32_e32 v14, v33, v95
	s_waitcnt vmcnt(5)
	v_fmac_f32_e32 v8, v18, v96
	v_fmac_f32_e32 v9, v26, v96
	v_fmac_f32_e32 v14, v34, v96
	s_waitcnt vmcnt(4)
	v_fmac_f32_e32 v8, v19, v97
	v_fmac_f32_e32 v9, v27, v97
	v_fmac_f32_e32 v14, v35, v97
	s_waitcnt vmcnt(3)
	v_fmac_f32_e32 v8, v20, v98
	v_fmac_f32_e32 v9, v28, v98
	v_fmac_f32_e32 v14, v36, v98
	s_waitcnt vmcnt(2)
	v_fmac_f32_e32 v8, v21, v99
	v_fmac_f32_e32 v9, v29, v99
	v_fmac_f32_e32 v14, v37, v99
	s_waitcnt vmcnt(1)
	v_fmac_f32_e32 v8, v22, v100
	v_fmac_f32_e32 v9, v30, v100
	v_fmac_f32_e32 v14, v38, v100
	s_waitcnt vmcnt(0)
	v_fmac_f32_e32 v8, v23, v101
	v_fmac_f32_e32 v9, v31, v101
	v_fmac_f32_e32 v14, v39, v101
	v_add_u32_e32 v15, 0x80, v15
	s_cmp_eq_u32 s12, 0x600000
	s_cbranch_scc0 .LBB0_3232
	ds_write2st64_b32 v11, v8, v9 offset0:48 offset1:50
	ds_write_b32 v11, v14 offset:13312
	s_waitcnt lgkmcnt(0)
	s_barrier
	s_and_saveexec_b64 s[12:13], vcc
	s_cbranch_execz .LBB0_3230
	v_readlane_b32 s56, v254, 40
	v_readlane_b32 s66, v254, 50
	v_readlane_b32 s67, v254, 51
	s_mul_i32 s17, s15, 0x6000
	s_mov_b64 s[10:11], s[66:67]
	s_mul_hi_i32 s16, s15, 0x6000
	s_add_u32 s17, s10, s17
	s_addc_u32 s22, s11, s16
	s_add_u32 s16, s17, s2
	s_addc_u32 s17, s22, s3
	global_load_dword v16, v0, s[16:17]
	ds_read_b32 v17, v10 offset:12288
	ds_read2st64_b32 v[6:7], v12 offset0:54 offset1:60
	ds_read_b32 v18, v12 offset:16896
	v_mad_i64_i32 v[8:9], s[16:17], s15, 3, v[2:3]
	v_mov_b64_e32 v[14:15], s[0:1]
	v_mad_u64_u32 v[14:15], s[16:17], v8, s23, v[14:15]
	s_waitcnt lgkmcnt(1)
	v_add_f32_e32 v6, v17, v6
	v_mad_i32_i24 v15, v9, s23, v15
	v_add_f32_e32 v6, v6, v7
	v_lshl_add_u64 v[8:9], v[14:15], 0, s[2:3]
	s_waitcnt lgkmcnt(0)
	v_add_f32_e32 v6, v6, v18
	v_readlane_b32 s57, v254, 41
	v_readlane_b32 s58, v254, 42
	v_readlane_b32 s59, v254, 43
	v_readlane_b32 s60, v254, 44
	v_readlane_b32 s61, v254, 45
	v_readlane_b32 s62, v254, 46
	v_readlane_b32 s63, v254, 47
	v_readlane_b32 s64, v254, 48
	v_readlane_b32 s65, v254, 49
	v_readlane_b32 s68, v254, 52
	v_readlane_b32 s69, v254, 53
	v_readlane_b32 s70, v254, 54
	v_readlane_b32 s71, v254, 55
	s_waitcnt vmcnt(0)
	v_add_f32_e32 v14, v6, v16
	v_lshl_add_u64 v[6:7], v[8:9], 0, v[0:1]
	global_store_dword v[6:7], v14, off
	s_branch .LBB0_3230
